# redundant clamped items skipped in coarse attention and weight conversion; scan remainder items on the last 64 virtual blocks so coarse attention and scan remainders run on different workgroups
# speedup vs baseline: 1.0030x; 1.0030x over previous
; DI void run_phase(int ph, char* smem) {
;     ...
;             const int n4 = NB * 6 * 2;
;             for (int k = 0; k < (n4 + G - 1) / G; ++k) {
;                 int it = bid + k * G; if (it >= n4) it = n4 - 1;
;                 const int qt = it & 1, pair = it >> 1, b = pair / 6, hh = pair % 6;
;                 if (hh < 4) attn_item<32>(p, l, b, hh, qt, 1, smh); else attn_item<64>(p, l, b, hh - 4, qt, 1, smh);
;             }
.LBB0_173:
	v_readlane_b32 s2, v253, 5
	s_mul_i32 s6, s15, s2
	v_readlane_b32 s2, v253, 2
	s_add_i32 s6, s6, s2
	s_cmpk_gt_i32 s6, 0x5f
	s_cbranch_scc1 .LBB0_199
	s_and_b32 s17, s6, 1
	s_ashr_i32 s6, s6, 1
	s_mul_hi_i32 s18, s6, 0x2aaaaaab
	s_lshr_b32 s7, s18, 31
	s_add_i32 s18, s18, s7
	s_mul_i32 s7, s18, 6
	s_sub_i32 s16, s6, s7
	s_cmp_gt_i32 s16, 3
	s_mov_b64 s[6:7], -1
	s_cbranch_scc1 .LBB0_175
	s_and_b64 vcc, exec, s[6:7]
	s_cbranch_vccz .LBB0_172
	s_branch .LBB0_188

; DI void phase_prologue(const Params& p, char* smem) {
;     ...
;     for (int k = 0; k < (2 * 5184 + G - 1) / G; ++k) {
;         int it = bid + k * G; if (it >= 2 * 5184) it = 2 * 5184 - 1;
;         const int l = it / 5184; int r = it % 5184;
;         const float* src; bf16_t* dst = p.WB + (size_t)l * W_LAYER; int K, N, kind, ntn;
;         if (r < 1408) { src = p.ffn1_wi + (size_t)l * 1024 * 5632; dst += W_WI1; K = 1024; N = 5632; kind = 1; ntn = 88; }
;         else if ((r -= 1408) < 704) { src = p.ffn1_wo + (size_t)l * 2816 * 1024; dst += W_WO1; K = 2816; N = 1024; kind = 0; ntn = 16; }
;         else if ((r -= 704) < 1408) { src = p.ffn2_wi + (size_t)l * 1024 * 5632; dst += W_WI2; K = 1024; N = 5632; kind = 1; ntn = 88; }
;         else if ((r -= 1408) < 704) { src = p.ffn2_wo + (size_t)l * 2816 * 1024; dst += W_WO2; K = 2816; N = 1024; kind = 0; ntn = 16; }
;         else if ((r -= 704) < 704) { src = p.w_in + (size_t)l * 1024 * 2576; dst += W_WIN; K = 1024; N = 2576; kind = 2; ntn = 44; }
;         else { r -= 704; src = p.w_out + (size_t)l * 1024 * 1024; dst += W_WOUT; K = 1024; N = 1024; kind = 0; ntn = 16; }
.LBB0_630:
	s_cmpk_gt_i32 s16, 0x287f
	s_cbranch_scc1 .LBB0_664
	s_mov_b32 s0, s16
	s_mul_hi_i32 s1, s0, 0x1948b0fd
	s_lshr_b32 s4, s1, 31
	s_ashr_i32 s1, s1, 9
	s_add_i32 s12, s1, s4
	v_readlane_b32 s76, v253, 49
	s_mul_i32 s1, s12, 0x1440
	v_readlane_b32 s77, v253, 50
	s_sub_i32 s18, s0, s1
	s_ashr_i32 s13, s12, 31
	s_mul_i32 s1, s12, 0x2880000
	s_mov_b64 s[4:5], s[76:77]
	s_mul_hi_i32 s0, s12, 0x2880000
	s_add_u32 s10, s4, s1
	s_addc_u32 s11, s5, s0
	s_cmpk_gt_i32 s18, 0x57f
	s_mov_b64 s[14:15], -1
	v_readlane_b32 s78, v253, 51
	v_readlane_b32 s79, v253, 52
	v_readlane_b32 s80, v253, 53
	v_readlane_b32 s81, v253, 54
	v_readlane_b32 s82, v253, 55
	v_readlane_b32 s83, v253, 56
	v_readlane_b32 s84, v253, 57
	v_readlane_b32 s85, v253, 58
	v_readlane_b32 s86, v253, 59
	v_readlane_b32 s87, v253, 60
	v_readlane_b32 s88, v253, 61
	v_readlane_b32 s89, v253, 62
	v_readlane_b32 s90, v253, 63
	v_readlane_b32 s91, v254, 0
	s_cbranch_scc0 .LBB0_647
	s_cmpk_gt_u32 s18, 0x83f
	s_cbranch_scc0 .LBB0_644
	s_cmpk_gt_u32 s18, 0xdbf
	s_cbranch_scc0 .LBB0_641
	s_cmpk_gt_u32 s18, 0x107f
	s_mov_b64 s[4:5], -1
	s_cbranch_scc0 .LBB0_638
	s_cmpk_gt_u32 s18, 0x133f
	s_cbranch_scc0 .LBB0_636
	s_add_i32 s19, s18, 0xffffecc0
	s_lshl_b64 s[0:1], s[12:13], 22
	s_add_u32 s8, s66, s0
	s_addc_u32 s9, s67, s1
	s_add_u32 s0, s10, 0x2680000
	s_addc_u32 s1, s11, 0
	s_mov_b64 s[4:5], 0
